# gMLP unit loop: all global loads of a unit issued at the top of the iteration (one round trip instead of five)
# baseline (speedup 1.0000x reference)
; #define LAS __attribute__((address_space(3)))
; __device__ __forceinline__ float bflo(unsigned u) { return __uint_as_float(u << 16); }
; __device__ __forceinline__ float bfhi(unsigned u) { return __uint_as_float(u & 0xffff0000u); }
; __device__ __forceinline__ unsigned short f2bf(float f) { return (unsigned short)(pk2(f, 0.f) & 0xffffu); }
; __device__ __forceinline__ void gmlp_unit(LAS unsigned char* lds, int unit, const bf16* U, const bf16* Vb, bf16* Y, const float* vs1, const float* vs2,
;                                           const float* lnw, const float* lnb, const float* bs) {
;     ...
;     const size_t m0 = (size_t)bn * 128; const int c0 = g * 128;
;     const int t = 16 * w + l16;
;     v4u uu[4], gg[4];
; #pragma unroll
;     for (int j = 0; j < 4; ++j) { const size_t off = (m0 + t) * 1024 + c0 + 32 * j + 8 * g4; uu[j] = *(const v4u*)(U + off); gg[j] = *(const v4u*)(Y + off); }
;     {
;         const int s = tid >> 2, cq = (tid & 3) * 32;
;         const size_t row = m0 + s;
;         const float mean = vs1[row] * (1.f / 1024.f); const float var = vs2[row] * (1.f / 1024.f) - mean * mean; const float rstd = rsqrtf(fmaxf(var, 0.f) + EPS);
; #pragma unroll
;         for (int j = 0; j < 4; ++j) {
;             const int cc = cq + 8 * j;
;             const v4u vr = *(const v4u*)(Vb + row * 1024 + c0 + cc);
;             const f32x4 w0 = *(const f32x4*)(lnw + c0 + cc), w1 = *(const f32x4*)(lnw + c0 + cc + 4), b0 = *(const f32x4*)(lnb + c0 + cc), b1 = *(const f32x4*)(lnb + c0 + cc + 4);
;             LAS bf16* vd = Vt + cc * 136 + s;
;             vd[0 * 136] = f2bf((bflo(vr.x) - mean) * rstd * w0[0] + b0[0]); vd[1 * 136] = f2bf((bfhi(vr.x) - mean) * rstd * w0[1] + b0[1]);
;             vd[2 * 136] = f2bf((bflo(vr.y) - mean) * rstd * w0[2] + b0[2]); vd[3 * 136] = f2bf((bfhi(vr.y) - mean) * rstd * w0[3] + b0[3]);
;             vd[4 * 136] = f2bf((bflo(vr.z) - mean) * rstd * w1[0] + b1[0]); vd[5 * 136] = f2bf((bfhi(vr.z) - mean) * rstd * w1[1] + b1[1]);
;             vd[6 * 136] = f2bf((bflo(vr.w) - mean) * rstd * w1[2] + b1[2]); vd[7 * 136] = f2bf((bfhi(vr.w) - mean) * rstd * w1[3] + b1[3]);
;         }
.LBB0_765:
	v_mov_b32_e32 v1, v145
	s_ashr_i32 s0, s7, 3
	v_readfirstlane_b32 s2, v1
	s_ashr_i32 s2, s2, 2
	s_ashr_i32 s1, s0, 31
	v_bfi_b32 v84, -16, s2, v1
	s_lshl_b64 s[0:1], s[0:1], 7
	v_ashrrev_i32_e32 v85, 31, v84
	v_lshl_add_u64 v[82:83], s[0:1], 0, v[84:85]
	v_lshlrev_b64 v[2:3], 10, v[82:83]
	v_ashrrev_i32_e32 v34, 2, v1
	v_lshlrev_b32_e32 v35, 5, v1
	v_bfe_u32 v88, v1, 4, 2
	v_or_b32_e32 v2, s26, v2
	v_and_b32_e32 v90, 0x60, v35
	v_ashrrev_i32_e32 v35, 31, v34
	v_or_b32_e32 v3, s27, v3
	v_lshl_or_b32 v2, v88, 3, v2
	v_lshl_add_u64 v[36:37], s[0:1], 0, v[34:35]
	v_readlane_b32 s0, v251, 21
	v_lshlrev_b64 v[2:3], 1, v[2:3]
	v_lshlrev_b64 v[38:39], 2, v[36:37]
	v_readlane_b32 s1, v251, 22
	v_lshl_add_u64 v[4:5], s[34:35], 0, v[2:3]
	global_load_dwordx4 v[30:33], v[4:5], off
	v_lshl_add_u64 v[40:41], s[0:1], 0, v[38:39]
	global_load_dword v197, v[40:41], off
	v_lshl_add_u64 v[4:5], s[50:51], 0, v[2:3]
	global_load_dwordx4 v[26:29], v[4:5], off
	v_or_b32_e32 v4, 64, v2
	v_mov_b32_e32 v5, v3
	v_lshl_add_u64 v[6:7], s[34:35], 0, v[4:5]
	v_lshl_add_u64 v[4:5], s[50:51], 0, v[4:5]
	global_load_dwordx4 v[22:25], v[6:7], off
	global_load_dwordx4 v[18:21], v[4:5], off
	v_or_b32_e32 v4, 0x80, v2
	v_mov_b32_e32 v5, v3
	v_readlane_b32 s0, v251, 23
	v_lshl_add_u64 v[6:7], s[34:35], 0, v[4:5]
	v_lshl_add_u64 v[4:5], s[50:51], 0, v[4:5]
	v_or_b32_e32 v2, 0xc0, v2
	v_readlane_b32 s1, v251, 24
	global_load_dwordx4 v[14:17], v[6:7], off
	global_load_dwordx4 v[10:13], v[4:5], off
	v_lshl_add_u64 v[4:5], s[34:35], 0, v[2:3]
	v_lshl_add_u64 v[2:3], s[50:51], 0, v[2:3]
	v_lshl_add_u64 v[38:39], s[0:1], 0, v[38:39]
	global_load_dwordx4 v[6:9], v[4:5], off
	global_load_dword v196, v[38:39], off
	global_load_dwordx4 v[2:5], v[2:3], off
	v_lshlrev_b64 v[36:37], 11, v[36:37]
	v_readlane_b32 s36, v251, 5
	s_lshl_b64 s[2:3], s[26:27], 2
	v_readlane_b32 s42, v251, 11
	v_readlane_b32 s43, v251, 12
	v_readlane_b32 s44, v251, 13
	v_readlane_b32 s45, v251, 14
	v_lshlrev_b32_e32 v89, 2, v90
	v_readlane_b32 s48, v251, 17
	v_readlane_b32 s49, v251, 18
	v_readlane_b32 s50, v251, 19
	v_readlane_b32 s51, v251, 20
	v_readlane_b32 s50, v255, 24
	v_readlane_b32 s51, v255, 25
	v_readlane_b32 s37, v251, 6
	v_readlane_b32 s38, v251, 7
	v_readlane_b32 s39, v251, 8
	v_readlane_b32 s40, v251, 9
	v_readlane_b32 s41, v251, 10
	v_readlane_b32 s46, v251, 15
	v_readlane_b32 s47, v251, 16
	v_readlane_b32 s0, v253, 0
	v_readlane_b32 s1, v253, 1
	v_lshlrev_b32_e32 v235, 1, v34
	v_lshlrev_b32_e32 v34, 1, v90
	v_lshl_add_u64 v[36:37], s[0:1], 0, v[36:37]
	s_lshl_b64 s[0:1], s[26:27], 1
	v_lshl_add_u64 v[36:37], v[36:37], 0, s[0:1]
	v_mov_b32_e32 v35, v0
	v_lshl_add_u64 v[46:47], v[36:37], 0, v[34:35]
	s_add_u32 s4, s42, s2
	global_load_dwordx4 v[34:37], v[46:47], off offset:48
	global_load_dwordx4 v[38:41], v[46:47], off offset:32
	global_load_dwordx4 v[42:45], v[46:47], off offset:16
	global_load_dwordx4 v[54:57], v[46:47], off
	s_addc_u32 s5, s43, s3
	s_add_u32 s2, s44, s2
	s_addc_u32 s3, s45, s3
	global_load_dwordx4 v[46:49], v89, s[4:5] offset:48
	global_load_dwordx4 v[58:61], v89, s[4:5] offset:32
	global_load_dwordx4 v[66:69], v89, s[4:5] offset:16
	global_load_dwordx4 v[74:77], v89, s[4:5]
	global_load_dwordx4 v[50:53], v89, s[2:3] offset:48
	global_load_dwordx4 v[62:65], v89, s[2:3] offset:32
	global_load_dwordx4 v[70:73], v89, s[2:3] offset:16
	global_load_dwordx4 v[78:81], v89, s[2:3]
	global_load_dwordx4 v[200:203], v89, s[4:5] offset:112
	global_load_dwordx4 v[204:207], v89, s[4:5] offset:96
	global_load_dwordx4 v[208:211], v89, s[4:5] offset:80
	global_load_dwordx4 v[224:227], v89, s[4:5] offset:64
	global_load_dwordx4 v[212:215], v89, s[2:3] offset:112
	global_load_dwordx4 v[216:219], v89, s[2:3] offset:96
	global_load_dwordx4 v[220:223], v89, s[2:3] offset:80
	global_load_dwordx4 v[228:231], v89, s[2:3] offset:64
	v_add_u32_e32 v198, s26, v84
	v_ashrrev_i32_e32 v199, 31, v198
	v_lshl_add_u64 v[198:199], v[198:199], 2, s[48:49]
	global_load_dword v232, v[198:199], off
	v_mul_u32_u24_e32 v90, 0x110, v90
	s_add_i32 s7, s7, s84
	s_waitcnt vmcnt(0)
	v_mul_f32_e32 v86, 0x3a800000, v196
	v_mul_f32_e32 v87, 0x3a800000, v197
	v_fma_f32 v233, -v87, v87, v86
	v_max_f32_e32 v233, 0, v233
	v_add_f32_e32 v233, 0x358637bd, v233
	v_cmp_gt_f32_e32 vcc, s33, v233
	v_mul_f32_e32 v234, 0x4b800000, v233
	s_nop 1
	v_cndmask_b32_e32 v233, v233, v234, vcc
	v_rsq_f32_e32 v233, v233
	s_nop 0
	v_mul_f32_e32 v234, 0x45800000, v233
	v_cndmask_b32_e32 v85, v233, v234, vcc
	v_add3_u32 v86, 0, v235, v90
	v_lshlrev_b32_e32 v90, 16, v54
	v_and_b32_e32 v54, 0xffff0000, v54
	v_sub_f32_e32 v54, v54, v87
	v_mul_f32_e32 v54, v54, v85
	v_fma_f32 v54, v75, v54, v79
	v_cvt_pk_bf16_f32 v54, v54, s0
	ds_write_b16 v86, v54 offset:35088
	v_lshlrev_b32_e32 v54, 16, v55
	v_sub_f32_e32 v54, v54, v87
	v_mul_f32_e32 v54, v54, v85
	v_fma_f32 v54, v76, v54, v80
	v_cvt_pk_bf16_f32 v54, v54, s0
	ds_write_b16 v86, v54 offset:35360
	v_and_b32_e32 v54, 0xffff0000, v55
	v_sub_f32_e32 v54, v54, v87
	v_mul_f32_e32 v54, v54, v85
	v_fmac_f32_e32 v81, v77, v54
	v_cvt_pk_bf16_f32 v54, v81, s0
	ds_write_b16 v86, v54 offset:35632
	v_lshlrev_b32_e32 v54, 16, v56
	v_sub_f32_e32 v54, v54, v87
	v_mul_f32_e32 v54, v54, v85
	v_fma_f32 v54, v66, v54, v70
	v_cvt_pk_bf16_f32 v54, v54, s0
	ds_write_b16 v86, v54 offset:35904
	v_and_b32_e32 v54, 0xffff0000, v56
	v_sub_f32_e32 v54, v54, v87
	v_mul_f32_e32 v54, v54, v85
	v_fma_f32 v54, v67, v54, v71
	v_cvt_pk_bf16_f32 v54, v54, s0
	ds_write_b16 v86, v54 offset:36176
	v_lshlrev_b32_e32 v54, 16, v57
	v_sub_f32_e32 v54, v54, v87
	v_mul_f32_e32 v54, v54, v85
	v_fma_f32 v54, v68, v54, v72
; #define LAS __attribute__((address_space(3)))
; __device__ __forceinline__ float bflo(unsigned u) { return __uint_as_float(u << 16); }
; __device__ __forceinline__ float bfhi(unsigned u) { return __uint_as_float(u & 0xffff0000u); }
; __device__ __forceinline__ unsigned short f2bf(float f) { return (unsigned short)(pk2(f, 0.f) & 0xffffu); }
; #define LBAR() do { asm volatile("s_waitcnt lgkmcnt(0)" ::: "memory"); __builtin_amdgcn_s_barrier(); asm volatile("" ::: "memory"); } while (0)
; __device__ __forceinline__ void gmlp_unit(LAS unsigned char* lds, int unit, const bf16* U, const bf16* Vb, bf16* Y, const float* vs1, const float* vs2,
;                                           const float* lnw, const float* lnb, const float* bs) {
;     ...
;         for (int j = 0; j < 4; ++j) {
;             const int cc = cq + 8 * j;
;             const v4u vr = *(const v4u*)(Vb + row * 1024 + c0 + cc);
;             const f32x4 w0 = *(const f32x4*)(lnw + c0 + cc), w1 = *(const f32x4*)(lnw + c0 + cc + 4), b0 = *(const f32x4*)(lnb + c0 + cc), b1 = *(const f32x4*)(lnb + c0 + cc + 4);
;             LAS bf16* vd = Vt + cc * 136 + s;
;             vd[0 * 136] = f2bf((bflo(vr.x) - mean) * rstd * w0[0] + b0[0]); vd[1 * 136] = f2bf((bfhi(vr.x) - mean) * rstd * w0[1] + b0[1]);
;             vd[2 * 136] = f2bf((bflo(vr.y) - mean) * rstd * w0[2] + b0[2]); vd[3 * 136] = f2bf((bfhi(vr.y) - mean) * rstd * w0[3] + b0[3]);
;             vd[4 * 136] = f2bf((bflo(vr.z) - mean) * rstd * w1[0] + b1[0]); vd[5 * 136] = f2bf((bfhi(vr.z) - mean) * rstd * w1[1] + b1[1]);
;             vd[6 * 136] = f2bf((bflo(vr.w) - mean) * rstd * w1[2] + b1[2]); vd[7 * 136] = f2bf((bfhi(vr.w) - mean) * rstd * w1[3] + b1[3]);
;         }
;     }
;     LBAR();
	v_cvt_pk_bf16_f32 v54, v54, s0
	ds_write_b16 v86, v54 offset:36448
	v_and_b32_e32 v54, 0xffff0000, v57
	v_sub_f32_e32 v54, v54, v87
	v_mul_f32_e32 v54, v54, v85
	v_fmac_f32_e32 v73, v69, v54
	v_cvt_pk_bf16_f32 v54, v73, s0
	ds_write_b16 v86, v54 offset:36720
	v_lshlrev_b32_e32 v54, 16, v42
	v_and_b32_e32 v42, 0xffff0000, v42
	v_sub_f32_e32 v42, v42, v87
	v_mul_f32_e32 v42, v85, v42
	v_fma_f32 v42, v59, v42, v63
	v_cvt_pk_bf16_f32 v42, v42, s0
	ds_write_b16 v86, v42 offset:37264
	v_lshlrev_b32_e32 v42, 16, v43
	v_sub_f32_e32 v42, v42, v87
	v_mul_f32_e32 v42, v85, v42
	v_fma_f32 v42, v60, v42, v64
	v_cvt_pk_bf16_f32 v42, v42, s0
	ds_write_b16 v86, v42 offset:37536
	v_and_b32_e32 v42, 0xffff0000, v43
	v_sub_f32_e32 v42, v42, v87
	v_mul_f32_e32 v42, v85, v42
	v_fmac_f32_e32 v65, v61, v42
	v_cvt_pk_bf16_f32 v42, v65, s0
	ds_write_b16 v86, v42 offset:37808
	v_lshlrev_b32_e32 v42, 16, v44
	v_sub_f32_e32 v42, v42, v87
	v_mul_f32_e32 v42, v85, v42
	v_fma_f32 v42, v46, v42, v50
	v_cvt_pk_bf16_f32 v42, v42, s0
	ds_write_b16 v86, v42 offset:38080
	v_and_b32_e32 v42, 0xffff0000, v44
	v_sub_f32_e32 v42, v42, v87
	v_mul_f32_e32 v42, v85, v42
	v_fma_f32 v42, v47, v42, v51
	v_cvt_pk_bf16_f32 v42, v42, s0
	ds_write_b16 v86, v42 offset:38352
	v_lshlrev_b32_e32 v42, 16, v45
	v_sub_f32_e32 v42, v42, v87
	v_mul_f32_e32 v42, v85, v42
	v_fma_f32 v42, v48, v42, v52
	v_cvt_pk_bf16_f32 v42, v42, s0
	ds_write_b16 v86, v42 offset:38624
	v_and_b32_e32 v42, 0xffff0000, v45
	v_sub_f32_e32 v90, v90, v87
	v_sub_f32_e32 v54, v54, v87
	v_sub_f32_e32 v42, v42, v87
	v_mul_f32_e32 v90, v90, v85
	v_mul_f32_e32 v54, v85, v54
	v_mul_f32_e32 v42, v85, v42
	v_fma_f32 v74, v74, v90, v78
	v_fma_f32 v54, v58, v54, v62
	v_fmac_f32_e32 v53, v49, v42
	v_cvt_pk_bf16_f32 v74, v74, s0
	v_cvt_pk_bf16_f32 v54, v54, s0
	v_cvt_pk_bf16_f32 v42, v53, s0
	ds_write_b16 v86, v74 offset:34816
	ds_write_b16 v86, v54 offset:36992
	ds_write_b16 v86, v42 offset:38896
	v_lshlrev_b32_e32 v74, 16, v38
	v_and_b32_e32 v38, 0xffff0000, v38
	v_sub_f32_e32 v38, v38, v87
	v_mul_f32_e32 v38, v85, v38
	v_sub_f32_e32 v74, v74, v87
	v_mul_f32_e32 v74, v85, v74
	s_movk_i32 s2, 0x110
	v_fma_f32 v38, v225, v38, v229
	v_cvt_pk_bf16_f32 v38, v38, s0
	ds_write_b16 v86, v38 offset:39440
	v_lshlrev_b32_e32 v38, 16, v39
	v_sub_f32_e32 v38, v38, v87
	v_mul_f32_e32 v38, v85, v38
	v_fma_f32 v38, v226, v38, v230
	v_cvt_pk_bf16_f32 v38, v38, s0
	ds_write_b16 v86, v38 offset:39712
	v_and_b32_e32 v38, 0xffff0000, v39
	v_sub_f32_e32 v38, v38, v87
	v_mul_f32_e32 v38, v85, v38
	v_fmac_f32_e32 v231, v227, v38
	v_cvt_pk_bf16_f32 v38, v231, s0
	ds_write_b16 v86, v38 offset:39984
	v_lshlrev_b32_e32 v38, 16, v40
	v_sub_f32_e32 v38, v38, v87
	v_mul_f32_e32 v38, v85, v38
	v_fma_f32 v38, v208, v38, v220
	v_cvt_pk_bf16_f32 v38, v38, s0
	ds_write_b16 v86, v38 offset:40256
	v_and_b32_e32 v38, 0xffff0000, v40
	v_sub_f32_e32 v38, v38, v87
	v_mul_f32_e32 v38, v85, v38
	v_fma_f32 v38, v209, v38, v221
	v_cvt_pk_bf16_f32 v38, v38, s0
	ds_write_b16 v86, v38 offset:40528
	v_lshlrev_b32_e32 v38, 16, v41
	v_sub_f32_e32 v38, v38, v87
	v_mul_f32_e32 v38, v85, v38
	v_fma_f32 v38, v210, v38, v222
	v_cvt_pk_bf16_f32 v38, v38, s0
	ds_write_b16 v86, v38 offset:40800
	v_and_b32_e32 v38, 0xffff0000, v41
	v_sub_f32_e32 v38, v38, v87
	v_mul_f32_e32 v38, v85, v38
	v_fmac_f32_e32 v223, v211, v38
	v_cvt_pk_bf16_f32 v38, v223, s0
	ds_write_b16 v86, v38 offset:41072
	v_lshlrev_b32_e32 v38, 16, v34
	v_and_b32_e32 v34, 0xffff0000, v34
	v_sub_f32_e32 v34, v34, v87
	v_mul_f32_e32 v34, v85, v34
	v_fma_f32 v34, v205, v34, v217
	v_cvt_pk_bf16_f32 v34, v34, s0
	ds_write_b16 v86, v34 offset:41616
	v_lshlrev_b32_e32 v34, 16, v35
	v_sub_f32_e32 v34, v34, v87
	v_mul_f32_e32 v34, v85, v34
	v_fma_f32 v34, v206, v34, v218
	v_cvt_pk_bf16_f32 v34, v34, s0
	ds_write_b16 v86, v34 offset:41888
	v_and_b32_e32 v34, 0xffff0000, v35
	v_sub_f32_e32 v34, v34, v87
	v_mul_f32_e32 v34, v85, v34
	v_fmac_f32_e32 v219, v207, v34
	v_cvt_pk_bf16_f32 v34, v219, s0
	ds_write_b16 v86, v34 offset:42160
	v_lshlrev_b32_e32 v34, 16, v36
	v_sub_f32_e32 v34, v34, v87
	v_mul_f32_e32 v34, v85, v34
	v_fma_f32 v34, v200, v34, v212
	v_cvt_pk_bf16_f32 v34, v34, s0
	ds_write_b16 v86, v34 offset:42432
	v_and_b32_e32 v34, 0xffff0000, v36
	v_sub_f32_e32 v34, v34, v87
	v_mul_f32_e32 v34, v85, v34
	v_fma_f32 v34, v201, v34, v213
	v_cvt_pk_bf16_f32 v34, v34, s0
	ds_write_b16 v86, v34 offset:42704
	v_lshlrev_b32_e32 v34, 16, v37
	v_sub_f32_e32 v34, v34, v87
	v_mul_f32_e32 v34, v85, v34
	v_fma_f32 v34, v202, v34, v214
	v_cvt_pk_bf16_f32 v34, v34, s0
	ds_write_b16 v86, v34 offset:42976
	v_and_b32_e32 v34, 0xffff0000, v37
	v_sub_f32_e32 v38, v38, v87
	v_sub_f32_e32 v34, v34, v87
	v_mul_f32_e32 v38, v85, v38
	v_mul_f32_e32 v34, v85, v34
	v_fma_f32 v224, v224, v74, v228
	v_fma_f32 v38, v204, v38, v216
	v_fmac_f32_e32 v215, v203, v34
	v_cvt_pk_bf16_f32 v224, v224, s0
	v_cvt_pk_bf16_f32 v38, v38, s0
	v_cvt_pk_bf16_f32 v34, v215, s0
	v_add_u32_e32 v50, s26, v84
	ds_write_b16 v86, v224 offset:39168
	ds_write_b16 v86, v38 offset:41344
	ds_write_b16 v86, v34 offset:43248
	v_mul_lo_u32 v34, v84, s2
	v_lshlrev_b32_e32 v54, 4, v88
	v_ashrrev_i32_e32 v51, 31, v50
	s_waitcnt lgkmcnt(0)
	s_barrier
; #define LAS __attribute__((address_space(3)))
; __device__ __forceinline__ float bflo(unsigned u) { return __uint_as_float(u << 16); }
; __device__ __forceinline__ float bfhi(unsigned u) { return __uint_as_float(u & 0xffff0000u); }
; __device__ __forceinline__ unsigned pk2(float lo, float hi) { f32x2_t v = {lo, hi}; bf16x2_t b = __builtin_convertvector(v, bf16x2_t); return __builtin_bit_cast(unsigned, b); }
; __device__ __forceinline__ f32x4 mfma16(bf16x8 a, bf16x8 b, f32x4 c) { return __builtin_amdgcn_mfma_f32_16x16x32_bf16(a, b, c, 0, 0, 0); }
; __device__ __forceinline__ void gmlp_unit(LAS unsigned char* lds, int unit, const bf16* U, const bf16* Vb, bf16* Y, const float* vs1, const float* vs2,
;                                           const float* lnw, const float* lnb, const float* bs) {
;     ...
;     bf16x8 bw[4];
; #pragma unroll
;     for (int ks = 0; ks < 4; ++ks) bw[ks] = *(const LAS bf16x8*)(Wa + (16 * w + l16) * 136 + 32 * ks + 8 * g4);
;     const float bias = bs[g * 128 + t];
; #pragma unroll
;     for (int j = 0; j < 4; ++j) {
;         const int crow = 32 * j + 8 * (l16 >> 2) + (l16 & 3);
;         f32x4 e4 = (f32x4){0.f, 0.f, 0.f, 0.f}, o4 = e4;
; #pragma unroll
;         for (int ks = 0; ks < 4; ++ks) {
;             const bf16x8 ae = *(const LAS bf16x8*)(Vt + crow * 136 + 32 * ks + 8 * g4), ao = *(const LAS bf16x8*)(Vt + (crow + 4) * 136 + 32 * ks + 8 * g4);
;             e4 = mfma16(ae, bw[ks], e4); o4 = mfma16(ao, bw[ks], o4);
;         }
;         const size_t off = (m0 + t) * 1024 + c0 + 32 * j + 8 * g4;
;         const v4u u4 = uu[j], g4v = gg[j];
;         v4u y;
;         y.x = pk2(bflo(u4.x) * (e4[0] + bias) * bflo(g4v.x), bfhi(u4.x) * (e4[1] + bias) * bfhi(g4v.x)); y.y = pk2(bflo(u4.y) * (e4[2] + bias) * bflo(g4v.y), bfhi(u4.y) * (e4[3] + bias) * bfhi(g4v.y));
;         y.z = pk2(bflo(u4.z) * (o4[0] + bias) * bflo(g4v.z), bfhi(u4.z) * (o4[1] + bias) * bfhi(g4v.z)); y.w = pk2(bflo(u4.w) * (o4[2] + bias) * bflo(g4v.w), bfhi(u4.w) * (o4[3] + bias) * bfhi(g4v.w));
;         *(v4u*)(Y + off) = y;
	v_add3_u32 v34, 0, v34, v54
	v_lshl_add_u64 v[50:51], v[50:51], 2, s[48:49]
	ds_read_b128 v[46:49], v34
	ds_read_b128 v[42:45], v34 offset:64
	ds_read_b128 v[38:41], v34 offset:128
	ds_read_b128 v[34:37], v34 offset:192
	v_mov_b32_e32 v50, v232
	v_lshlrev_b32_e32 v51, 1, v1
	v_and_b32_e32 v1, 3, v1
	v_and_or_b32 v1, v51, 24, v1
	v_lshlrev_b64 v[52:53], 11, v[82:83]
	v_lshl_add_u64 v[52:53], s[50:51], 0, v[52:53]
	v_mul_u32_u24_e32 v1, 0x110, v1
	v_lshl_add_u64 v[52:53], v[52:53], 0, s[0:1]
	v_mov_b32_e32 v55, v0
	v_add3_u32 v1, 0, v1, v54
	v_lshl_add_u64 v[52:53], v[52:53], 0, v[54:55]
	ds_read_b128 v[54:57], v1 offset:34816
	ds_read_b128 v[58:61], v1 offset:35904
	ds_read_b128 v[62:65], v1 offset:34880
	ds_read_b128 v[66:69], v1 offset:35968
	s_waitcnt lgkmcnt(3)
	v_mfma_f32_16x16x32_bf16 v[54:57], v[54:57], v[46:49], 0
	v_readlane_b32 s0, v254, 54
	s_add_i32 s6, s6, s0
	s_cmpk_gt_i32 s7, 0x3ff
	s_waitcnt lgkmcnt(2)
	v_mfma_f32_16x16x32_bf16 v[58:61], v[58:61], v[46:49], 0
	s_waitcnt lgkmcnt(1)
	v_mfma_f32_16x16x32_bf16 v[54:57], v[62:65], v[42:45], v[54:57]
	s_waitcnt lgkmcnt(0)
	v_mfma_f32_16x16x32_bf16 v[58:61], v[66:69], v[42:45], v[58:61]
	ds_read_b128 v[62:65], v1 offset:34944
	ds_read_b128 v[66:69], v1 offset:36032
	s_waitcnt lgkmcnt(1)
	v_mfma_f32_16x16x32_bf16 v[54:57], v[62:65], v[38:41], v[54:57]
	s_waitcnt lgkmcnt(0)
	v_mfma_f32_16x16x32_bf16 v[58:61], v[66:69], v[38:41], v[58:61]
	ds_read_b128 v[62:65], v1 offset:35008
	ds_read_b128 v[66:69], v1 offset:36096
	s_waitcnt lgkmcnt(1)
	v_mfma_f32_16x16x32_bf16 v[54:57], v[62:65], v[34:37], v[54:57]
	v_lshlrev_b32_e32 v62, 16, v30
	v_and_b32_e32 v63, 0xffff0000, v30
	v_lshlrev_b32_e32 v30, 16, v31
	s_waitcnt lgkmcnt(0)
	v_mfma_f32_16x16x32_bf16 v[58:61], v[66:69], v[34:37], v[58:61]
	v_and_b32_e32 v31, 0xffff0000, v31
	s_waitcnt vmcnt(0)
	s_nop 0
	v_pk_add_f32 v[54:55], v[50:51], v[54:55] op_sel_hi:[0,1]
	v_pk_mul_f32 v[54:55], v[54:55], v[62:63]
	v_lshlrev_b32_e32 v62, 16, v26
	v_and_b32_e32 v63, 0xffff0000, v26
	v_pk_mul_f32 v[54:55], v[54:55], v[62:63]
	s_nop 0
	v_cvt_pk_bf16_f32 v26, v54, v55
	v_pk_add_f32 v[54:55], v[50:51], v[56:57] op_sel_hi:[0,1]
	v_pk_mul_f32 v[30:31], v[54:55], v[30:31]
	v_lshlrev_b32_e32 v54, 16, v27
	v_and_b32_e32 v55, 0xffff0000, v27
	v_pk_mul_f32 v[30:31], v[30:31], v[54:55]
	v_pk_add_f32 v[54:55], v[50:51], v[58:59] op_sel_hi:[0,1]
	v_cvt_pk_bf16_f32 v27, v30, v31
	v_lshlrev_b32_e32 v30, 16, v32
	v_and_b32_e32 v31, 0xffff0000, v32
	v_pk_mul_f32 v[30:31], v[54:55], v[30:31]
	v_lshlrev_b32_e32 v54, 16, v28
	v_and_b32_e32 v55, 0xffff0000, v28
	v_pk_mul_f32 v[30:31], v[30:31], v[54:55]
	s_nop 0
	v_cvt_pk_bf16_f32 v28, v30, v31
	v_lshlrev_b32_e32 v30, 16, v33
	v_and_b32_e32 v31, 0xffff0000, v33
	v_pk_add_f32 v[32:33], v[50:51], v[60:61] op_sel_hi:[0,1]
	v_pk_mul_f32 v[30:31], v[32:33], v[30:31]
	v_lshlrev_b32_e32 v32, 16, v29
	v_and_b32_e32 v33, 0xffff0000, v29
	v_pk_mul_f32 v[30:31], v[30:31], v[32:33]
	s_nop 0
	v_cvt_pk_bf16_f32 v29, v30, v31
	global_store_dwordx4 v[52:53], v[26:29], off
	ds_read_b128 v[26:29], v1 offset:43520
	ds_read_b128 v[30:33], v1 offset:44608
	ds_read_b128 v[54:57], v1 offset:43584
	ds_read_b128 v[58:61], v1 offset:44672
	s_waitcnt lgkmcnt(3)
	v_mfma_f32_16x16x32_bf16 v[26:29], v[26:29], v[46:49], 0
	s_waitcnt lgkmcnt(2)
	v_mfma_f32_16x16x32_bf16 v[30:33], v[30:33], v[46:49], 0
	s_waitcnt lgkmcnt(1)
	v_mfma_f32_16x16x32_bf16 v[26:29], v[54:57], v[42:45], v[26:29]
	s_waitcnt lgkmcnt(0)
	v_mfma_f32_16x16x32_bf16 v[30:33], v[58:61], v[42:45], v[30:33]
	ds_read_b128 v[54:57], v1 offset:43648
	ds_read_b128 v[58:61], v1 offset:44736
	s_waitcnt lgkmcnt(1)
	v_mfma_f32_16x16x32_bf16 v[26:29], v[54:57], v[38:41], v[26:29]
	s_waitcnt lgkmcnt(0)
	v_mfma_f32_16x16x32_bf16 v[30:33], v[58:61], v[38:41], v[30:33]
	ds_read_b128 v[54:57], v1 offset:43712
	ds_read_b128 v[58:61], v1 offset:44800
	s_waitcnt lgkmcnt(1)
	v_mfma_f32_16x16x32_bf16 v[26:29], v[54:57], v[34:37], v[26:29]
	v_lshlrev_b32_e32 v54, 16, v22
	v_and_b32_e32 v55, 0xffff0000, v22
	v_lshlrev_b32_e32 v22, 16, v23
	s_waitcnt lgkmcnt(0)
	v_mfma_f32_16x16x32_bf16 v[30:33], v[58:61], v[34:37], v[30:33]
	s_nop 2
	v_add_f32_e64 v26, v50, v26
	v_add_f32_e64 v27, v50, v27
	v_pk_mul_f32 v[26:27], v[26:27], v[54:55]
	v_lshlrev_b32_e32 v54, 16, v18
	v_and_b32_e32 v55, 0xffff0000, v18
	v_pk_mul_f32 v[26:27], v[26:27], v[54:55]
	v_and_b32_e32 v23, 0xffff0000, v23
	v_cvt_pk_bf16_f32 v18, v26, v27
	v_pk_add_f32 v[26:27], v[50:51], v[28:29] op_sel_hi:[0,1]
	v_pk_mul_f32 v[22:23], v[26:27], v[22:23]
	v_lshlrev_b32_e32 v26, 16, v19
	v_and_b32_e32 v27, 0xffff0000, v19
	v_pk_mul_f32 v[22:23], v[22:23], v[26:27]
	v_pk_add_f32 v[26:27], v[50:51], v[30:31] op_sel_hi:[0,1]
	v_cvt_pk_bf16_f32 v19, v22, v23
	v_lshlrev_b32_e32 v22, 16, v24
	v_and_b32_e32 v23, 0xffff0000, v24
	v_pk_mul_f32 v[22:23], v[26:27], v[22:23]
	v_lshlrev_b32_e32 v26, 16, v20
	v_and_b32_e32 v27, 0xffff0000, v20
	v_pk_mul_f32 v[22:23], v[22:23], v[26:27]
	s_nop 0
	v_cvt_pk_bf16_f32 v20, v22, v23
	v_lshlrev_b32_e32 v22, 16, v25
	v_and_b32_e32 v23, 0xffff0000, v25
	v_pk_add_f32 v[24:25], v[50:51], v[32:33] op_sel_hi:[0,1]
	v_pk_mul_f32 v[22:23], v[24:25], v[22:23]
	v_lshlrev_b32_e32 v24, 16, v21
	v_and_b32_e32 v25, 0xffff0000, v21
	v_pk_mul_f32 v[22:23], v[22:23], v[24:25]
	s_nop 0
	v_cvt_pk_bf16_f32 v21, v22, v23
	global_store_dwordx4 v[52:53], v[18:21], off offset:64
	ds_read_b128 v[18:21], v1 offset:52224
	ds_read_b128 v[22:25], v1 offset:53312
	ds_read_b128 v[26:29], v1 offset:52288
	ds_read_b128 v[30:33], v1 offset:53376
	s_waitcnt lgkmcnt(3)
; #define LAS __attribute__((address_space(3)))
; __device__ __forceinline__ float bflo(unsigned u) { return __uint_as_float(u << 16); }
; __device__ __forceinline__ float bfhi(unsigned u) { return __uint_as_float(u & 0xffff0000u); }
; __device__ __forceinline__ unsigned pk2(float lo, float hi) { f32x2_t v = {lo, hi}; bf16x2_t b = __builtin_convertvector(v, bf16x2_t); return __builtin_bit_cast(unsigned, b); }
; __device__ __forceinline__ f32x4 mfma16(bf16x8 a, bf16x8 b, f32x4 c) { return __builtin_amdgcn_mfma_f32_16x16x32_bf16(a, b, c, 0, 0, 0); }
; #define LBAR() do { asm volatile("s_waitcnt lgkmcnt(0)" ::: "memory"); __builtin_amdgcn_s_barrier(); asm volatile("" ::: "memory"); } while (0)
; __device__ __forceinline__ void gmlp_unit(LAS unsigned char* lds, int unit, const bf16* U, const bf16* Vb, bf16* Y, const float* vs1, const float* vs2,
;                                           const float* lnw, const float* lnb, const float* bs) {
;     ...
;     for (int j = 0; j < 4; ++j) {
;         const int crow = 32 * j + 8 * (l16 >> 2) + (l16 & 3);
;         f32x4 e4 = (f32x4){0.f, 0.f, 0.f, 0.f}, o4 = e4;
; #pragma unroll
;         for (int ks = 0; ks < 4; ++ks) {
;             const bf16x8 ae = *(const LAS bf16x8*)(Vt + crow * 136 + 32 * ks + 8 * g4), ao = *(const LAS bf16x8*)(Vt + (crow + 4) * 136 + 32 * ks + 8 * g4);
;             e4 = mfma16(ae, bw[ks], e4); o4 = mfma16(ao, bw[ks], o4);
;         }
;         const size_t off = (m0 + t) * 1024 + c0 + 32 * j + 8 * g4;
;         const v4u u4 = uu[j], g4v = gg[j];
;         v4u y;
;         y.x = pk2(bflo(u4.x) * (e4[0] + bias) * bflo(g4v.x), bfhi(u4.x) * (e4[1] + bias) * bfhi(g4v.x)); y.y = pk2(bflo(u4.y) * (e4[2] + bias) * bflo(g4v.y), bfhi(u4.y) * (e4[3] + bias) * bfhi(g4v.y));
;         y.z = pk2(bflo(u4.z) * (o4[0] + bias) * bflo(g4v.z), bfhi(u4.z) * (o4[1] + bias) * bfhi(g4v.z)); y.w = pk2(bflo(u4.w) * (o4[2] + bias) * bflo(g4v.w), bfhi(u4.w) * (o4[3] + bias) * bfhi(g4v.w));
;         *(v4u*)(Y + off) = y;
;     }
;     LBAR();
	v_mfma_f32_16x16x32_bf16 v[18:21], v[18:21], v[46:49], 0
	s_waitcnt lgkmcnt(2)
	v_mfma_f32_16x16x32_bf16 v[22:25], v[22:25], v[46:49], 0
	s_waitcnt lgkmcnt(1)
	v_mfma_f32_16x16x32_bf16 v[18:21], v[26:29], v[42:45], v[18:21]
	s_waitcnt lgkmcnt(0)
	v_mfma_f32_16x16x32_bf16 v[22:25], v[30:33], v[42:45], v[22:25]
	ds_read_b128 v[26:29], v1 offset:52352
	ds_read_b128 v[30:33], v1 offset:53440
	s_waitcnt lgkmcnt(1)
	v_mfma_f32_16x16x32_bf16 v[18:21], v[26:29], v[38:41], v[18:21]
	s_waitcnt lgkmcnt(0)
	v_mfma_f32_16x16x32_bf16 v[22:25], v[30:33], v[38:41], v[22:25]
	ds_read_b128 v[26:29], v1 offset:52416
	ds_read_b128 v[30:33], v1 offset:53504
	s_waitcnt lgkmcnt(1)
	v_mfma_f32_16x16x32_bf16 v[18:21], v[26:29], v[34:37], v[18:21]
	v_lshlrev_b32_e32 v26, 16, v14
	v_and_b32_e32 v27, 0xffff0000, v14
	v_lshlrev_b32_e32 v14, 16, v15
	s_waitcnt lgkmcnt(0)
	v_mfma_f32_16x16x32_bf16 v[22:25], v[30:33], v[34:37], v[22:25]
	s_nop 2
	v_add_f32_e64 v18, v50, v18
	v_add_f32_e64 v19, v50, v19
	v_pk_mul_f32 v[18:19], v[18:19], v[26:27]
	v_lshlrev_b32_e32 v26, 16, v10
	v_and_b32_e32 v27, 0xffff0000, v10
	v_pk_mul_f32 v[18:19], v[18:19], v[26:27]
	v_and_b32_e32 v15, 0xffff0000, v15
	v_cvt_pk_bf16_f32 v10, v18, v19
	v_pk_add_f32 v[18:19], v[50:51], v[20:21] op_sel_hi:[0,1]
	v_pk_mul_f32 v[14:15], v[18:19], v[14:15]
	v_lshlrev_b32_e32 v18, 16, v11
	v_and_b32_e32 v19, 0xffff0000, v11
	v_pk_mul_f32 v[14:15], v[14:15], v[18:19]
	v_pk_add_f32 v[18:19], v[50:51], v[22:23] op_sel_hi:[0,1]
	v_cvt_pk_bf16_f32 v11, v14, v15
	v_lshlrev_b32_e32 v14, 16, v16
	v_and_b32_e32 v15, 0xffff0000, v16
	v_pk_mul_f32 v[14:15], v[18:19], v[14:15]
	v_lshlrev_b32_e32 v18, 16, v12
	v_and_b32_e32 v19, 0xffff0000, v12
	v_pk_mul_f32 v[14:15], v[14:15], v[18:19]
	s_nop 0
	v_cvt_pk_bf16_f32 v12, v14, v15
	v_lshlrev_b32_e32 v14, 16, v17
	v_and_b32_e32 v15, 0xffff0000, v17
	v_pk_add_f32 v[16:17], v[50:51], v[24:25] op_sel_hi:[0,1]
	v_pk_mul_f32 v[14:15], v[16:17], v[14:15]
	v_lshlrev_b32_e32 v16, 16, v13
	v_and_b32_e32 v17, 0xffff0000, v13
	v_pk_mul_f32 v[14:15], v[14:15], v[16:17]
	s_nop 0
	v_cvt_pk_bf16_f32 v13, v14, v15
	global_store_dwordx4 v[52:53], v[10:13], off offset:128
	ds_read_b128 v[10:13], v1 offset:60928
	ds_read_b128 v[14:17], v1 offset:62016
	ds_read_b128 v[18:21], v1 offset:60992
	ds_read_b128 v[22:25], v1 offset:62080
	s_waitcnt lgkmcnt(3)
	v_mfma_f32_16x16x32_bf16 v[10:13], v[10:13], v[46:49], 0
	s_waitcnt lgkmcnt(2)
	v_mfma_f32_16x16x32_bf16 v[14:17], v[14:17], v[46:49], 0
	s_waitcnt lgkmcnt(1)
	v_mfma_f32_16x16x32_bf16 v[10:13], v[18:21], v[42:45], v[10:13]
	s_waitcnt lgkmcnt(0)
	v_mfma_f32_16x16x32_bf16 v[14:17], v[22:25], v[42:45], v[14:17]
	ds_read_b128 v[18:21], v1 offset:61056
	ds_read_b128 v[22:25], v1 offset:62144
	s_waitcnt lgkmcnt(1)
	v_mfma_f32_16x16x32_bf16 v[10:13], v[18:21], v[38:41], v[10:13]
	s_waitcnt lgkmcnt(0)
	v_mfma_f32_16x16x32_bf16 v[14:17], v[22:25], v[38:41], v[14:17]
	ds_read_b128 v[18:21], v1 offset:61120
	ds_read_b128 v[22:25], v1 offset:62208
	s_waitcnt lgkmcnt(1)
	v_mfma_f32_16x16x32_bf16 v[10:13], v[18:21], v[34:37], v[10:13]
	v_lshlrev_b32_e32 v18, 16, v6
	v_and_b32_e32 v19, 0xffff0000, v6
	v_lshlrev_b32_e32 v6, 16, v7
	s_waitcnt lgkmcnt(0)
	v_mfma_f32_16x16x32_bf16 v[14:17], v[22:25], v[34:37], v[14:17]
	s_nop 2
	v_add_f32_e64 v10, v50, v10
	v_add_f32_e64 v11, v50, v11
	v_pk_mul_f32 v[10:11], v[10:11], v[18:19]
	v_lshlrev_b32_e32 v18, 16, v2
	v_and_b32_e32 v19, 0xffff0000, v2
	v_pk_mul_f32 v[10:11], v[10:11], v[18:19]
	v_and_b32_e32 v7, 0xffff0000, v7
	v_cvt_pk_bf16_f32 v2, v10, v11
	v_pk_add_f32 v[10:11], v[50:51], v[12:13] op_sel_hi:[0,1]
	v_pk_mul_f32 v[6:7], v[10:11], v[6:7]
	v_lshlrev_b32_e32 v10, 16, v3
	v_and_b32_e32 v11, 0xffff0000, v3
	v_pk_mul_f32 v[6:7], v[6:7], v[10:11]
	v_pk_add_f32 v[10:11], v[50:51], v[14:15] op_sel_hi:[0,1]
	v_cvt_pk_bf16_f32 v3, v6, v7
	v_lshlrev_b32_e32 v6, 16, v8
	v_and_b32_e32 v7, 0xffff0000, v8
	v_pk_mul_f32 v[6:7], v[10:11], v[6:7]
	v_lshlrev_b32_e32 v10, 16, v4
	v_and_b32_e32 v11, 0xffff0000, v4
	v_pk_mul_f32 v[6:7], v[6:7], v[10:11]
	s_nop 0
	v_cvt_pk_bf16_f32 v4, v6, v7
	v_lshlrev_b32_e32 v6, 16, v9
	v_and_b32_e32 v7, 0xffff0000, v9
	v_pk_add_f32 v[8:9], v[50:51], v[16:17] op_sel_hi:[0,1]
	v_pk_mul_f32 v[6:7], v[8:9], v[6:7]
	v_lshlrev_b32_e32 v8, 16, v5
	v_and_b32_e32 v9, 0xffff0000, v5
	v_pk_mul_f32 v[6:7], v[6:7], v[8:9]
	s_nop 0
	v_cvt_pk_bf16_f32 v5, v6, v7
	global_store_dwordx4 v[52:53], v[2:5], off offset:192
	s_waitcnt lgkmcnt(0)
	s_barrier
	s_cbranch_scc1 .LBB0_762
